# attention steady loop: per-tile row-max/rescale test skipped under a runtime guard on the q/k norm gains (scores bounded by RMS norm); original path kept as fallback; plus combo2
# speedup vs baseline: 1.0223x; 1.0223x over previous
.LBB0_471:
	s_or_b64 exec, exec, s[0:1]
	v_readlane_b32 s0, v254, 41
	v_readlane_b32 s1, v254, 42
	s_andn2_b64 vcc, exec, s[0:1]
	s_waitcnt lgkmcnt(0)
	s_barrier
	v_readlane_b32 s100, v253, 31
	v_readlane_b32 s101, v253, 32
	s_cmp_gt_u32 s96, 2
	s_cselect_b32 s98, 0x100, 0
	v_and_b32_e32 v214, 63, v234
	v_lshl_add_u32 v214, v214, 2, s98
	s_nop 4
	global_load_dword v215, v214, s[100:101]
	v_readlane_b32 s100, v253, 33
	v_readlane_b32 s101, v253, 34
	s_nop 4
	global_load_dword v216, v214, s[100:101]
	s_waitcnt vmcnt(0)
	v_and_b32_e32 v215, 0x7fffffff, v215
	v_and_b32_e32 v216, 0x7fffffff, v216
	v_max_f32_e32 v215, v215, v216
	s_nop 1
	v_max_f32_dpp v215, v215, v215 quad_perm:[1,0,3,2] row_mask:0xf bank_mask:0xf bound_ctrl:1
	s_nop 1
	v_max_f32_dpp v215, v215, v215 quad_perm:[2,3,0,1] row_mask:0xf bank_mask:0xf bound_ctrl:1
	s_nop 1
	v_max_f32_dpp v215, v215, v215 row_half_mirror row_mask:0xf bank_mask:0xf bound_ctrl:1
	s_nop 1
	v_max_f32_dpp v215, v215, v215 row_mirror row_mask:0xf bank_mask:0xf bound_ctrl:1
	v_mov_b32_e32 v216, v215
	s_nop 1
	v_permlane16_swap_b32_e32 v215, v216
	v_max_f32_e32 v215, v215, v216
	v_mov_b32_e32 v216, v215
	s_nop 1
	v_permlane32_swap_b32_e32 v215, v216
	v_max_f32_e32 v215, v215, v216
	v_mul_f32_e32 v215, v215, v215
	s_nop 1
	v_readfirstlane_b32 s98, v215
	s_nop 3
	s_cmp_lt_u32 s98, 0x40800000
	s_cselect_b32 s99, 1, 0
	s_cbranch_vccnz .LBB0_474
	v_mov_b32_e32 v0, v234
	s_movk_i32 s0, 0x100
	v_ashrrev_i32_e32 v4, 8, v0
	v_cmp_gt_u32_e32 vcc, s0, v0
	v_ashrrev_i32_e32 v5, 31, v4
	v_readlane_b32 s0, v254, 43
	v_lshlrev_b64 v[2:3], 11, v[4:5]
	v_mov_b32_e32 v6, 2
	v_lshlrev_b64 v[4:5], 10, v[4:5]
	v_readlane_b32 s1, v254, 44
	v_lshl_add_u64 v[2:3], s[28:29], 0, v[2:3]
	v_lshlrev_b32_sdwa v0, v6, v0 dst_sel:DWORD dst_unused:UNUSED_PAD src0_sel:DWORD src1_sel:BYTE_0
	v_lshl_add_u64 v[4:5], s[0:1], 0, v[4:5]
	v_lshl_add_u64 v[2:3], v[2:3], 0, v[0:1]
	v_lshl_add_u64 v[4:5], v[4:5], 0, v[0:1]
	s_mov_b32 s1, 0
	v_mov_b32_e32 v70, 0
	s_movk_i32 s0, 0x67

.LBB0_485:
	v_add_u32_e32 v190, s4, v203
	ds_read_b64_tr_b16 v[178:179], v190 offset:24576
	ds_read_b64_tr_b16 v[180:181], v190 offset:25088
	s_waitcnt lgkmcnt(9)
	v_mfma_f32_32x32x16_bf16 v[98:113], v[174:177], v[142:145], v[34:49]
	v_add_f32_e32 v82, v66, v67
	v_add_f32_e32 v82, v68, v82
	v_add_f32_e32 v82, v69, v82
	v_add_f32_e32 v82, v70, v82
	v_add_f32_e32 v82, v71, v82
	v_cvt_pk_bf16_f32 v138, v66, v67
	v_cvt_pk_bf16_f32 v139, v68, v69
	ds_read_b64_tr_b16 v[174:175], v190 offset:28672
	ds_read_b64_tr_b16 v[176:177], v190 offset:29184
	v_add_f32_e32 v66, v72, v82
	s_waitcnt lgkmcnt(10)
	v_mfma_f32_32x32x16_bf16 v[82:97], v[170:173], v[142:145], v[34:49]
	v_add_f32_e32 v66, v73, v66
	v_add_f32_e32 v66, v74, v66
	v_add_f32_e32 v114, v75, v66
	v_cvt_pk_bf16_f32 v140, v70, v71
	v_cvt_pk_bf16_f32 v141, v72, v73
	ds_read_b64_tr_b16 v[66:67], v190 offset:25600
	ds_read_b64_tr_b16 v[68:69], v190 offset:26112
	s_waitcnt lgkmcnt(11)
	v_mfma_f32_32x32x16_bf16 v[98:113], v[166:169], v[134:137], v[98:113]
	v_add_f32_e32 v70, v76, v114
	v_add_f32_e32 v70, v77, v70
	v_add_f32_e32 v70, v78, v70
	v_add_f32_e32 v114, v79, v70
	v_cvt_pk_bf16_f32 v130, v74, v75
	v_cvt_pk_bf16_f32 v131, v76, v77
	ds_read_b64_tr_b16 v[70:71], v190 offset:29696
	ds_read_b64_tr_b16 v[72:73], v190 offset:30208
	s_waitcnt lgkmcnt(12)
	v_mfma_f32_32x32x16_bf16 v[82:97], v[162:165], v[134:137], v[82:97]
	v_add_f32_e32 v74, v80, v114
	v_add_f32_e32 v74, v81, v74
	v_add_f32_e32 v74, v50, v74
	v_add_f32_e32 v114, v51, v74
	v_cvt_pk_bf16_f32 v132, v78, v79
	v_cvt_pk_bf16_f32 v133, v80, v81
	ds_read_b64_tr_b16 v[74:75], v190 offset:26624
	ds_read_b64_tr_b16 v[76:77], v190 offset:27136
	s_waitcnt lgkmcnt(13)
	v_mfma_f32_32x32x16_bf16 v[98:113], v[158:161], v[126:129], v[98:113]
	v_add_f32_e32 v78, v52, v114
	v_add_f32_e32 v78, v53, v78
	v_add_f32_e32 v78, v54, v78
	v_add_f32_e32 v78, v55, v78
	v_cvt_pk_bf16_f32 v122, v50, v51
	v_cvt_pk_bf16_f32 v123, v52, v53
	ds_read_b64_tr_b16 v[50:51], v190 offset:30720
	ds_read_b64_tr_b16 v[52:53], v190 offset:31232
	s_waitcnt lgkmcnt(14)
	v_mfma_f32_32x32x16_bf16 v[82:97], v[154:157], v[126:129], v[82:97]
	v_add_f32_e32 v78, v56, v78
	v_add_f32_e32 v78, v57, v78
	v_add_f32_e32 v78, v58, v78
	v_add_f32_e32 v78, v59, v78
	v_cvt_pk_bf16_f32 v124, v54, v55
	v_cvt_pk_bf16_f32 v125, v56, v57
	ds_read_b64_tr_b16 v[54:55], v190 offset:27648
	ds_read_b64_tr_b16 v[56:57], v190 offset:28160
	s_waitcnt lgkmcnt(14)
	v_mfma_f32_32x32x16_bf16 v[98:113], v[150:153], v[118:121], v[98:113]
	v_add_f32_e32 v78, v60, v78
	v_add_f32_e32 v78, v61, v78
	v_add_f32_e32 v78, v62, v78
	v_add_f32_e32 v78, v63, v78
	v_cvt_pk_bf16_f32 v114, v58, v59
	v_cvt_pk_bf16_f32 v115, v60, v61
	ds_read_b64_tr_b16 v[58:59], v190 offset:31744
	ds_read_b64_tr_b16 v[60:61], v190 offset:32256
	v_mfma_f32_32x32x16_bf16 v[82:97], v[146:149], v[118:121], v[82:97]
	v_add_f32_e32 v78, v64, v78
	v_add_f32_e32 v78, v65, v78
	v_add_f32_e32 v78, 0, v78
	v_cvt_pk_bf16_f32 v116, v62, v63
	v_cvt_pk_bf16_f32 v117, v64, v65
	v_lshl_add_u64 v[62:63], v[188:189], 0, s[80:81]
	s_add_i32 s4, s11, s46
	s_mov_b32 s5, m0
	s_mov_b32 m0, s4
	s_nop 0
	global_load_lds_dwordx4 v[62:63], off
	s_mov_b32 m0, s5
	v_lshl_add_u64 v[62:63], v[186:187], 0, s[80:81]
	s_add_i32 s4, s14, s47
	s_mov_b32 s5, m0
	s_mov_b32 m0, s4
	s_nop 0
	global_load_lds_dwordx4 v[62:63], off
	s_mov_b32 m0, s5
	s_cmp_lg_u32 s99, 0
	s_cbranch_scc1 .Lnomax_1
	v_max_f32_e32 v62, v99, v99
	v_max_f32_e32 v63, v98, v98
	v_max_f32_e32 v62, v63, v62
	v_max3_f32 v63, v100, v101, v83
	v_max3_f32 v62, v62, v82, v84
	v_max3_f32 v62, v62, v85, v102
	v_max3_f32 v63, v63, v104, v105
	v_max3_f32 v62, v62, v103, v86
	v_max3_f32 v63, v63, v88, v89
	v_max3_f32 v62, v62, v87, v106
	v_max3_f32 v63, v63, v108, v109
	v_max3_f32 v62, v62, v107, v90
	v_max3_f32 v63, v63, v92, v93
	v_max3_f32 v62, v62, v91, v110
	v_max3_f32 v63, v63, v112, v113
	v_max3_f32 v62, v62, v111, v94
	v_max3_f32 v63, v63, v96, v97
	v_max3_f32 v62, v62, v95, v63
	v_mov_b32_e32 v63, v62
	s_nop 1
	v_permlane32_swap_b32_e32 v62, v63
	v_max_f32_e32 v63, v63, v63
	v_max_f32_e32 v62, v62, v62
	v_max_f32_e32 v62, v62, v63
	v_cmp_lt_f32_e32 vcc, s93, v62
	s_cmp_lg_u64 vcc, 0
	v_add_f32_e32 v190, v205, v78
	s_cselect_b64 s[4:5], -1, 0
	s_cbranch_vccnz .LBB0_493

.LBB0_488:
	s_add_i32 s4, s14, 0x2000
	s_cmpk_lg_i32 s14, 0x4000
	s_cselect_b32 s50, s4, 0
	v_add_u32_e32 v192, s11, v203
	ds_read_b64_tr_b16 v[150:151], v192 offset:24576
	ds_read_b64_tr_b16 v[152:153], v192 offset:25088
	s_waitcnt lgkmcnt(9)
	v_mfma_f32_32x32x16_bf16 v[66:81], v[62:65], v[142:145], v[34:49]
	v_add_f32_e32 v50, v98, v99
	v_add_f32_e32 v50, v100, v50
	v_add_f32_e32 v50, v101, v50
	v_add_f32_e32 v50, v102, v50
	v_add_f32_e32 v50, v103, v50
	v_cvt_pk_bf16_f32 v138, v98, v99
	v_cvt_pk_bf16_f32 v139, v100, v101
	ds_read_b64_tr_b16 v[146:147], v192 offset:28672
	ds_read_b64_tr_b16 v[148:149], v192 offset:29184
	v_add_f32_e32 v50, v104, v50
	v_add_f32_e32 v50, v105, v50
	v_add_f32_e32 v50, v106, v50
	v_add_f32_e32 v114, v107, v50
	s_waitcnt lgkmcnt(10)
	v_mfma_f32_32x32x16_bf16 v[50:65], v[174:177], v[142:145], v[34:49]
	v_cvt_pk_bf16_f32 v140, v102, v103
	v_cvt_pk_bf16_f32 v141, v104, v105
	ds_read_b64_tr_b16 v[98:99], v192 offset:25600
	ds_read_b64_tr_b16 v[100:101], v192 offset:26112
	s_waitcnt lgkmcnt(11)
	v_mfma_f32_32x32x16_bf16 v[66:81], v[178:181], v[134:137], v[66:81]
	v_add_f32_e32 v102, v108, v114
	v_add_f32_e32 v102, v109, v102
	v_add_f32_e32 v102, v110, v102
	v_add_f32_e32 v114, v111, v102
	v_cvt_pk_bf16_f32 v130, v106, v107
	v_cvt_pk_bf16_f32 v131, v108, v109
	ds_read_b64_tr_b16 v[102:103], v192 offset:29696
	ds_read_b64_tr_b16 v[104:105], v192 offset:30208
	s_waitcnt lgkmcnt(12)
	v_mfma_f32_32x32x16_bf16 v[50:65], v[170:173], v[134:137], v[50:65]
	v_add_f32_e32 v106, v112, v114
	v_add_f32_e32 v106, v113, v106
	v_add_f32_e32 v106, v82, v106
	v_add_f32_e32 v114, v83, v106
	v_cvt_pk_bf16_f32 v132, v110, v111
	v_cvt_pk_bf16_f32 v133, v112, v113
	ds_read_b64_tr_b16 v[106:107], v192 offset:26624
	ds_read_b64_tr_b16 v[108:109], v192 offset:27136
	s_waitcnt lgkmcnt(13)
	v_mfma_f32_32x32x16_bf16 v[66:81], v[166:169], v[126:129], v[66:81]
	v_add_f32_e32 v110, v84, v114
	v_add_f32_e32 v110, v85, v110
	v_add_f32_e32 v110, v86, v110
	v_add_f32_e32 v110, v87, v110
	v_cvt_pk_bf16_f32 v122, v82, v83
	v_cvt_pk_bf16_f32 v123, v84, v85
	ds_read_b64_tr_b16 v[82:83], v192 offset:30720
	ds_read_b64_tr_b16 v[84:85], v192 offset:31232
	s_waitcnt lgkmcnt(14)
	v_mfma_f32_32x32x16_bf16 v[50:65], v[162:165], v[126:129], v[50:65]
	v_add_f32_e32 v110, v88, v110
	v_add_f32_e32 v110, v89, v110
	v_add_f32_e32 v110, v90, v110
	v_add_f32_e32 v110, v91, v110
	v_cvt_pk_bf16_f32 v124, v86, v87
	v_cvt_pk_bf16_f32 v125, v88, v89
	ds_read_b64_tr_b16 v[86:87], v192 offset:27648
	ds_read_b64_tr_b16 v[88:89], v192 offset:28160
	s_waitcnt lgkmcnt(14)
	v_mfma_f32_32x32x16_bf16 v[66:81], v[158:161], v[118:121], v[66:81]
	v_add_f32_e32 v110, v92, v110
	v_add_f32_e32 v110, v93, v110
	v_add_f32_e32 v110, v94, v110
	v_add_f32_e32 v110, v95, v110
	v_cvt_pk_bf16_f32 v114, v90, v91
	v_cvt_pk_bf16_f32 v115, v92, v93
	ds_read_b64_tr_b16 v[90:91], v192 offset:31744
	ds_read_b64_tr_b16 v[92:93], v192 offset:32256
	v_mfma_f32_32x32x16_bf16 v[50:65], v[154:157], v[118:121], v[50:65]
	v_add_f32_e32 v110, v96, v110
	v_add_f32_e32 v110, v97, v110
	v_add_f32_e32 v110, 0, v110
	v_cvt_pk_bf16_f32 v116, v94, v95
	v_cvt_pk_bf16_f32 v117, v96, v97
	s_cmp_lg_u32 s99, 0
	s_cbranch_scc1 .Lnomax_2a
	v_max_f32_e32 v94, v67, v67
	v_max_f32_e32 v95, v66, v66
	v_max_f32_e32 v94, v95, v94
	s_nop 3
	v_max3_f32 v95, v68, v69, v51
	v_max3_f32 v94, v94, v50, v52
	v_max3_f32 v94, v94, v53, v70
	v_max3_f32 v95, v95, v72, v73
	v_max3_f32 v94, v94, v71, v54
	v_max3_f32 v95, v95, v56, v57
	v_max3_f32 v94, v94, v55, v74
	v_max3_f32 v95, v95, v76, v77
	v_max3_f32 v94, v94, v75, v58
	v_max3_f32 v95, v95, v60, v61
	v_max3_f32 v94, v94, v59, v78
	v_max3_f32 v95, v95, v80, v81
	v_max3_f32 v94, v94, v79, v62
	v_max3_f32 v95, v95, v64, v65
	v_max3_f32 v94, v94, v63, v95
	v_mov_b32_e32 v95, v94
	s_nop 1
	v_permlane32_swap_b32_e32 v94, v95
	v_max_f32_e32 v95, v95, v95
	v_max_f32_e32 v94, v94, v94
.Lnomax_2a:
	s_add_i32 s4, s14, s46
	s_mov_b32 s5, m0
	s_mov_b32 m0, s4
	s_nop 0
	global_load_lds_dwordx4 v[188:189], off
	s_mov_b32 m0, s5
	v_max_f32_e32 v94, v94, v95
	s_add_i32 s4, s50, s47
	s_mov_b32 s5, m0
	s_mov_b32 m0, s4
	s_nop 0
	global_load_lds_dwordx4 v[186:187], off
	s_mov_b32 m0, s5
	s_cmp_lg_u32 s99, 0
	s_cbranch_scc1 .Lnomax_2b
	v_cmp_lt_f32_e32 vcc, s93, v94
	s_cmp_lg_u64 vcc, 0
	v_add_f32_e32 v205, v190, v110
	s_cselect_b64 s[4:5], -1, 0
	s_cbranch_vccnz .LBB0_496

.Lnomax_1:
	v_add_f32_e32 v190, v205, v78
	s_mov_b64 s[4:5], 0
	s_branch .LBB0_486
.Lnomax_2b:
	v_add_f32_e32 v205, v190, v110
	s_mov_b64 s[4:5], 0
	s_branch .LBB0_489
